# phase-13 bf16 epilogue: the 8 per-row-group sum-of-squares loads issued up front (one wait) instead of load+vmcnt(0) per group
# speedup vs baseline: 1.1668x; 1.0005x over previous
; DEV unsigned cvt_pk_bf16(float lo, float hi) { unsigned r; asm volatile("v_cvt_pk_bf16_f32 %0, %1, %2" : "=v"(r) : "v"(lo), "v"(hi)); return r; }
;     DEV void operator()(const Acc& acc, const Unit& u, int wr, int wc, int fr, int fq, LAS unsigned char*) const {
;     ...
;         int colt = u.pn * 256; bf16_t* base = O0; if (split && colt >= split) { base = O1; colt -= split; }
;         const int row0 = rowbase + u.pz * zrows + u.pm * 256 + wr * 64 + fr, col0 = colt + wc * 32 + 8 * fq;
; #pragma unroll
;         for (int ai = 0; ai < 2; ++ai)
; #pragma unroll
;             for (int m = 0; m < 4; ++m) { const int row = row0 + ai * 128 + m * 16; bf16_t* rowp = base + (size_t)row * ldc + col0;
;                 const float sc = rs ? scale / sqrtf(rs[(size_t)row * 2 + rsi] * rsdiv + EPS) : scale;
; #pragma unroll
;                 for (int bj = 0; bj < 2; ++bj) { const f32x4 v0 = acc[ai][bj][m][0] * sc, v1 = acc[ai][bj][m][1] * sc; u32x4 w;
;                     w.x = cvt_pk_bf16(v0[0], v0[1]); w.y = cvt_pk_bf16(v0[2], v0[3]); w.z = cvt_pk_bf16(v1[0], v1[1]); w.w = cvt_pk_bf16(v1[2], v1[3]);
;                     *(u32x4*)(rowp + bj * 128) = w; } }
.LBB0_2056:
	v_mov_b32_e32 v140, v147
	v_mov_b32_e32 v142, v145
	s_lshl_b32 s4, s6, 8
	s_add_i32 s4, s4, s48
	v_add_u32_e32 v140, s4, v140
	v_cndmask_b32_e64 v143, 0, 1, s[22:23]
	v_ashrrev_i32_e32 v141, 31, v140
	v_mov_b32_e32 v144, 1.0
	v_cmp_ne_u32_e64 s[4:5], 1, v143
	s_andn2_b64 vcc, exec, s[22:23]
	v_mov_b32_e32 v146, 1.0
	v_readlane_b32 s27, v251, 14
	s_cbranch_vccnz .LBB0_2058
	v_lshl_add_u64 v[150:151], v[140:141], 3, s[20:21]
	global_load_dword v143, v[150:151], off
	global_load_dword v190, v[150:151], off offset:128
	global_load_dword v191, v[150:151], off offset:256
	global_load_dword v192, v[150:151], off offset:384
	global_load_dword v193, v[150:151], off offset:1024
	global_load_dword v194, v[150:151], off offset:1152
	global_load_dword v195, v[150:151], off offset:1280
	global_load_dword v196, v[150:151], off offset:1408
	s_waitcnt vmcnt(0)
	v_fma_f32 v143, s27, v143, v180
	v_mul_f32_e32 v146, 0x4f800000, v143
	v_cmp_gt_f32_e32 vcc, s78, v143
	s_nop 1
	v_cndmask_b32_e32 v143, v143, v146, vcc
	v_sqrt_f32_e32 v146, v143
	s_nop 0
	v_add_u32_e32 v150, -1, v146
	v_add_u32_e32 v151, 1, v146
	v_fma_f32 v152, -v150, v146, v143
	v_fma_f32 v153, -v151, v146, v143
	v_cmp_ge_f32_e64 s[6:7], 0, v152
	s_nop 1
	v_cndmask_b32_e64 v146, v146, v150, s[6:7]
	v_cmp_lt_f32_e64 s[6:7], 0, v153
	s_nop 1
	v_cndmask_b32_e64 v146, v146, v151, s[6:7]
	v_mul_f32_e32 v150, 0x37800000, v146
	v_cndmask_b32_e32 v146, v146, v150, vcc
	v_cmp_class_f32_e32 vcc, v143, v181
	s_nop 1
	v_cndmask_b32_e32 v143, v146, v143, vcc
	v_div_scale_f32 v146, s[6:7], v143, v143, 1.0
	v_rcp_f32_e32 v150, v146
	v_div_scale_f32 v151, vcc, 1.0, v143, 1.0
	v_fma_f32 v152, -v146, v150, 1.0
	v_fmac_f32_e32 v150, v152, v150
	v_mul_f32_e32 v152, v151, v150
	v_fma_f32 v153, -v146, v152, v151
	v_fmac_f32_e32 v152, v153, v150
	v_fma_f32 v146, -v146, v152, v151
	v_div_fmas_f32 v146, v146, v150, v152
	v_div_fixup_f32 v146, v146, v143, 1.0
.LBB0_2058:
	s_lshl_b32 s25, s38, 8
	s_cmp_lt_i32 s25, s73
	v_readlane_b32 s40, v249, 24
	s_cselect_b64 s[6:7], -1, 0
	v_readlane_b32 s41, v249, 25
	s_or_b64 s[6:7], s[40:41], s[6:7]
	s_and_b64 s[6:7], s[6:7], exec
	s_cselect_b32 s6, s75, s69
	s_cselect_b32 s7, s74, s68
	v_mov_b32_e32 v150, s7
	v_mov_b32_e32 v151, s6
	s_cselect_b32 s6, 0, s73
	s_or_b32 s7, s25, s49
	s_sub_i32 s6, s7, s6
	v_lshl_add_u32 v142, v142, 3, s6
	v_ashrrev_i32_e32 v143, 31, v142
	v_lshl_add_u64 v[142:143], v[142:143], 1, v[150:151]
	v_mul_lo_u32 v152, s59, v140
	v_mul_lo_u32 v141, s58, v141
	v_mad_u64_u32 v[150:151], s[6:7], s58, v140, 0
	v_add3_u32 v151, v151, v141, v152
	v_lshl_add_u64 v[150:151], v[150:151], 1, v[142:143]
	v_pk_mul_f32 v[128:129], v[128:129], v[146:147] op_sel_hi:[1,0]
	v_pk_mul_f32 v[126:127], v[126:127], v[146:147] op_sel_hi:[1,0]
	v_pk_mul_f32 v[152:153], v[124:125], v[146:147] op_sel_hi:[1,0]
	v_pk_mul_f32 v[124:125], v[122:123], v[146:147] op_sel_hi:[1,0]
	v_cvt_pk_bf16_f32 v122, v126, v127
	v_cvt_pk_bf16_f32 v123, v128, v129
	v_pk_mul_f32 v[118:119], v[118:119], v[146:147] op_sel_hi:[1,0]
	v_cvt_pk_bf16_f32 v124, v124, v125
	v_cvt_pk_bf16_f32 v125, v152, v153
	global_store_dwordx4 v[150:151], v[122:125], off
	v_pk_mul_f32 v[120:121], v[120:121], v[146:147] op_sel_hi:[1,0]
	s_and_b64 vcc, exec, s[4:5]
	v_pk_mul_f32 v[122:123], v[116:117], v[146:147] op_sel_hi:[1,0]
	v_pk_mul_f32 v[116:117], v[114:115], v[146:147] op_sel_hi:[1,0]
	v_cvt_pk_bf16_f32 v114, v118, v119
	v_cvt_pk_bf16_f32 v115, v120, v121
	s_nop 0
	v_cvt_pk_bf16_f32 v116, v116, v117
	v_cvt_pk_bf16_f32 v117, v122, v123
	global_store_dwordx4 v[150:151], v[114:117], off offset:256
	s_nop 1
	v_add_u32_e32 v114, 16, v140
	v_ashrrev_i32_e32 v115, 31, v114
	s_cbranch_vccnz .LBB0_2060
	v_lshl_add_u64 v[116:117], v[114:115], 3, s[20:21]
	v_mov_b32_e32 v116, v190
	v_fma_f32 v116, s27, v116, v180
	v_mul_f32_e32 v117, 0x4f800000, v116
	v_cmp_gt_f32_e32 vcc, s78, v116
	s_nop 1
	v_cndmask_b32_e32 v116, v116, v117, vcc
	v_sqrt_f32_e32 v117, v116
	s_nop 0
	v_add_u32_e32 v118, -1, v117
	v_add_u32_e32 v119, 1, v117
	v_fma_f32 v120, -v118, v117, v116
	v_fma_f32 v121, -v119, v117, v116
	v_cmp_ge_f32_e64 s[6:7], 0, v120
	s_nop 1
	v_cndmask_b32_e64 v117, v117, v118, s[6:7]
	v_cmp_lt_f32_e64 s[6:7], 0, v121
	s_nop 1
	v_cndmask_b32_e64 v117, v117, v119, s[6:7]
	v_mul_f32_e32 v118, 0x37800000, v117
	v_cndmask_b32_e32 v117, v117, v118, vcc
	v_cmp_class_f32_e32 vcc, v116, v181
	s_nop 1
	v_cndmask_b32_e32 v116, v117, v116, vcc
	v_div_scale_f32 v117, s[6:7], v116, v116, 1.0
	v_rcp_f32_e32 v118, v117
	v_div_scale_f32 v119, vcc, 1.0, v116, 1.0
	v_fma_f32 v120, -v117, v118, 1.0
	v_fmac_f32_e32 v118, v120, v118
	v_mul_f32_e32 v120, v119, v118
	v_fma_f32 v121, -v117, v120, v119
	v_fmac_f32_e32 v120, v121, v118
	v_fma_f32 v117, -v117, v120, v119
	v_div_fmas_f32 v117, v117, v118, v120
	v_div_fixup_f32 v144, v117, v116, 1.0
; DEV unsigned cvt_pk_bf16(float lo, float hi) { unsigned r; asm volatile("v_cvt_pk_bf16_f32 %0, %1, %2" : "=v"(r) : "v"(lo), "v"(hi)); return r; }
;     DEV void operator()(const Acc& acc, const Unit& u, int wr, int wc, int fr, int fq, LAS unsigned char*) const {
;     ...
;         for (int ai = 0; ai < 2; ++ai)
; #pragma unroll
;             for (int m = 0; m < 4; ++m) { const int row = row0 + ai * 128 + m * 16; bf16_t* rowp = base + (size_t)row * ldc + col0;
;                 const float sc = rs ? scale / sqrtf(rs[(size_t)row * 2 + rsi] * rsdiv + EPS) : scale;
; #pragma unroll
;                 for (int bj = 0; bj < 2; ++bj) { const f32x4 v0 = acc[ai][bj][m][0] * sc, v1 = acc[ai][bj][m][1] * sc; u32x4 w;
;                     w.x = cvt_pk_bf16(v0[0], v0[1]); w.y = cvt_pk_bf16(v0[2], v0[3]); w.z = cvt_pk_bf16(v1[0], v1[1]); w.w = cvt_pk_bf16(v1[2], v1[3]);
;                     *(u32x4*)(rowp + bj * 128) = w; } }
.LBB0_2060:
	v_mul_lo_u32 v116, s59, v114
	v_mul_lo_u32 v117, s58, v115
	v_mad_u64_u32 v[114:115], s[6:7], s58, v114, 0
	v_add3_u32 v115, v115, v117, v116
	v_lshl_add_u64 v[114:115], v[114:115], 1, v[142:143]
	v_pk_mul_f32 v[112:113], v[112:113], v[144:145] op_sel_hi:[1,0]
	v_pk_mul_f32 v[110:111], v[110:111], v[144:145] op_sel_hi:[1,0]
	v_pk_mul_f32 v[116:117], v[108:109], v[144:145] op_sel_hi:[1,0]
	v_pk_mul_f32 v[108:109], v[106:107], v[144:145] op_sel_hi:[1,0]
	v_cvt_pk_bf16_f32 v106, v110, v111
	v_cvt_pk_bf16_f32 v107, v112, v113
	v_pk_mul_f32 v[104:105], v[104:105], v[144:145] op_sel_hi:[1,0]
	v_cvt_pk_bf16_f32 v108, v108, v109
	v_cvt_pk_bf16_f32 v109, v116, v117
	global_store_dwordx4 v[114:115], v[106:109], off
	v_pk_mul_f32 v[102:103], v[102:103], v[144:145] op_sel_hi:[1,0]
	s_and_b64 vcc, exec, s[4:5]
	v_pk_mul_f32 v[106:107], v[100:101], v[144:145] op_sel_hi:[1,0]
	v_pk_mul_f32 v[100:101], v[98:99], v[144:145] op_sel_hi:[1,0]
	v_cvt_pk_bf16_f32 v98, v102, v103
	v_cvt_pk_bf16_f32 v99, v104, v105
	v_mov_b32_e32 v102, 1.0
	v_cvt_pk_bf16_f32 v100, v100, v101
	v_cvt_pk_bf16_f32 v101, v106, v107
	global_store_dwordx4 v[114:115], v[98:101], off offset:256
	s_nop 1
	v_add_u32_e32 v100, 32, v140
	v_ashrrev_i32_e32 v101, 31, v100
	v_mov_b32_e32 v98, 1.0
	s_cbranch_vccnz .LBB0_2062
	v_lshl_add_u64 v[102:103], v[100:101], 3, s[20:21]
	v_mov_b32_e32 v99, v191
	v_fma_f32 v99, s27, v99, v180
	v_mul_f32_e32 v102, 0x4f800000, v99
	v_cmp_gt_f32_e32 vcc, s78, v99
	s_nop 1
	v_cndmask_b32_e32 v99, v99, v102, vcc
	v_sqrt_f32_e32 v102, v99
	s_nop 0
	v_add_u32_e32 v103, -1, v102
	v_add_u32_e32 v104, 1, v102
	v_fma_f32 v105, -v103, v102, v99
	v_fma_f32 v106, -v104, v102, v99
	v_cmp_ge_f32_e64 s[6:7], 0, v105
	s_nop 1
	v_cndmask_b32_e64 v102, v102, v103, s[6:7]
	v_cmp_lt_f32_e64 s[6:7], 0, v106
	s_nop 1
	v_cndmask_b32_e64 v102, v102, v104, s[6:7]
	v_mul_f32_e32 v103, 0x37800000, v102
	v_cndmask_b32_e32 v102, v102, v103, vcc
	v_cmp_class_f32_e32 vcc, v99, v181
	s_nop 1
	v_cndmask_b32_e32 v99, v102, v99, vcc
	v_div_scale_f32 v102, s[6:7], v99, v99, 1.0
	v_rcp_f32_e32 v103, v102
	v_div_scale_f32 v104, vcc, 1.0, v99, 1.0
	v_fma_f32 v105, -v102, v103, 1.0
	v_fmac_f32_e32 v103, v105, v103
	v_mul_f32_e32 v105, v104, v103
	v_fma_f32 v106, -v102, v105, v104
	v_fmac_f32_e32 v105, v106, v103
	v_fma_f32 v102, -v102, v105, v104
	v_div_fmas_f32 v102, v102, v103, v105
	v_div_fixup_f32 v102, v102, v99, 1.0
.LBB0_2062:
	v_mul_lo_u32 v99, s59, v100
	v_mul_lo_u32 v103, s58, v101
	v_mad_u64_u32 v[100:101], s[6:7], s58, v100, 0
	v_add3_u32 v101, v101, v103, v99
	v_lshl_add_u64 v[100:101], v[100:101], 1, v[142:143]
	v_pk_mul_f32 v[94:95], v[94:95], v[102:103] op_sel_hi:[1,0]
	v_pk_mul_f32 v[92:93], v[92:93], v[102:103] op_sel_hi:[1,0]
	v_pk_mul_f32 v[104:105], v[90:91], v[102:103] op_sel_hi:[1,0]
	v_pk_mul_f32 v[90:91], v[88:89], v[102:103] op_sel_hi:[1,0]
	v_cvt_pk_bf16_f32 v88, v92, v93
	v_cvt_pk_bf16_f32 v89, v94, v95
	v_pk_mul_f32 v[84:85], v[84:85], v[102:103] op_sel_hi:[1,0]
	v_cvt_pk_bf16_f32 v90, v90, v91
	v_cvt_pk_bf16_f32 v91, v104, v105
	global_store_dwordx4 v[100:101], v[88:91], off
	v_pk_mul_f32 v[86:87], v[86:87], v[102:103] op_sel_hi:[1,0]
	s_and_b64 vcc, exec, s[4:5]
	v_pk_mul_f32 v[88:89], v[82:83], v[102:103] op_sel_hi:[1,0]
	v_pk_mul_f32 v[82:83], v[80:81], v[102:103] op_sel_hi:[1,0]
	v_cvt_pk_bf16_f32 v80, v84, v85
	v_cvt_pk_bf16_f32 v81, v86, v87
	s_nop 0
	v_cvt_pk_bf16_f32 v82, v82, v83
	v_cvt_pk_bf16_f32 v83, v88, v89
	global_store_dwordx4 v[100:101], v[80:83], off offset:256
	s_nop 1
	v_add_u32_e32 v80, 48, v140
	v_ashrrev_i32_e32 v81, 31, v80
	s_cbranch_vccnz .LBB0_2064
	v_lshl_add_u64 v[82:83], v[80:81], 3, s[20:21]
	v_mov_b32_e32 v82, v192
	v_fma_f32 v82, s27, v82, v180
	v_mul_f32_e32 v83, 0x4f800000, v82
	v_cmp_gt_f32_e32 vcc, s78, v82
	s_nop 1
	v_cndmask_b32_e32 v82, v82, v83, vcc
	v_sqrt_f32_e32 v83, v82
	s_nop 0
	v_add_u32_e32 v84, -1, v83
	v_add_u32_e32 v85, 1, v83
	v_fma_f32 v86, -v84, v83, v82
	v_fma_f32 v87, -v85, v83, v82
	v_cmp_ge_f32_e64 s[6:7], 0, v86
	s_nop 1
	v_cndmask_b32_e64 v83, v83, v84, s[6:7]
	v_cmp_lt_f32_e64 s[6:7], 0, v87
	s_nop 1
	v_cndmask_b32_e64 v83, v83, v85, s[6:7]
	v_mul_f32_e32 v84, 0x37800000, v83
	v_cndmask_b32_e32 v83, v83, v84, vcc
	v_cmp_class_f32_e32 vcc, v82, v181
	s_nop 1
	v_cndmask_b32_e32 v82, v83, v82, vcc
	v_div_scale_f32 v83, s[6:7], v82, v82, 1.0
	v_rcp_f32_e32 v84, v83
	v_div_scale_f32 v85, vcc, 1.0, v82, 1.0
	v_fma_f32 v86, -v83, v84, 1.0
	v_fmac_f32_e32 v84, v86, v84
	v_mul_f32_e32 v86, v85, v84
	v_fma_f32 v87, -v83, v86, v85
	v_fmac_f32_e32 v86, v87, v84
	v_fma_f32 v83, -v83, v86, v85
	v_div_fmas_f32 v83, v83, v84, v86
	v_div_fixup_f32 v98, v83, v82, 1.0
; DEV unsigned cvt_pk_bf16(float lo, float hi) { unsigned r; asm volatile("v_cvt_pk_bf16_f32 %0, %1, %2" : "=v"(r) : "v"(lo), "v"(hi)); return r; }
;     DEV void operator()(const Acc& acc, const Unit& u, int wr, int wc, int fr, int fq, LAS unsigned char*) const {
;     ...
;         for (int ai = 0; ai < 2; ++ai)
; #pragma unroll
;             for (int m = 0; m < 4; ++m) { const int row = row0 + ai * 128 + m * 16; bf16_t* rowp = base + (size_t)row * ldc + col0;
;                 const float sc = rs ? scale / sqrtf(rs[(size_t)row * 2 + rsi] * rsdiv + EPS) : scale;
; #pragma unroll
;                 for (int bj = 0; bj < 2; ++bj) { const f32x4 v0 = acc[ai][bj][m][0] * sc, v1 = acc[ai][bj][m][1] * sc; u32x4 w;
;                     w.x = cvt_pk_bf16(v0[0], v0[1]); w.y = cvt_pk_bf16(v0[2], v0[3]); w.z = cvt_pk_bf16(v1[0], v1[1]); w.w = cvt_pk_bf16(v1[2], v1[3]);
;                     *(u32x4*)(rowp + bj * 128) = w; } }
.LBB0_2064:
	v_mul_lo_u32 v82, s59, v80
	v_mul_lo_u32 v83, s58, v81
	v_mad_u64_u32 v[80:81], s[6:7], s58, v80, 0
	v_add3_u32 v81, v81, v83, v82
	v_lshl_add_u64 v[80:81], v[80:81], 1, v[142:143]
	v_pk_mul_f32 v[78:79], v[78:79], v[98:99] op_sel_hi:[1,0]
	v_pk_mul_f32 v[76:77], v[76:77], v[98:99] op_sel_hi:[1,0]
	v_pk_mul_f32 v[82:83], v[74:75], v[98:99] op_sel_hi:[1,0]
	v_pk_mul_f32 v[74:75], v[72:73], v[98:99] op_sel_hi:[1,0]
	v_cvt_pk_bf16_f32 v72, v76, v77
	v_cvt_pk_bf16_f32 v73, v78, v79
	v_pk_mul_f32 v[70:71], v[70:71], v[98:99] op_sel_hi:[1,0]
	v_cvt_pk_bf16_f32 v74, v74, v75
	v_cvt_pk_bf16_f32 v75, v82, v83
	global_store_dwordx4 v[80:81], v[72:75], off
	v_pk_mul_f32 v[68:69], v[68:69], v[98:99] op_sel_hi:[1,0]
	s_and_b64 vcc, exec, s[4:5]
	v_pk_mul_f32 v[72:73], v[66:67], v[98:99] op_sel_hi:[1,0]
	v_pk_mul_f32 v[66:67], v[64:65], v[98:99] op_sel_hi:[1,0]
	v_cvt_pk_bf16_f32 v64, v68, v69
	v_cvt_pk_bf16_f32 v65, v70, v71
	v_mov_b32_e32 v68, 1.0
	v_cvt_pk_bf16_f32 v66, v66, v67
	v_cvt_pk_bf16_f32 v67, v72, v73
	global_store_dwordx4 v[80:81], v[64:67], off offset:256
	s_nop 1
	v_add_u32_e32 v66, 0x80, v140
	v_ashrrev_i32_e32 v67, 31, v66
	v_mov_b32_e32 v64, 1.0
	s_cbranch_vccnz .LBB0_2066
	v_lshl_add_u64 v[68:69], v[66:67], 3, s[20:21]
	v_mov_b32_e32 v65, v193
	v_fma_f32 v65, s27, v65, v180
	v_mul_f32_e32 v68, 0x4f800000, v65
	v_cmp_gt_f32_e32 vcc, s78, v65
	s_nop 1
	v_cndmask_b32_e32 v65, v65, v68, vcc
	v_sqrt_f32_e32 v68, v65
	s_nop 0
	v_add_u32_e32 v69, -1, v68
	v_add_u32_e32 v70, 1, v68
	v_fma_f32 v71, -v69, v68, v65
	v_fma_f32 v72, -v70, v68, v65
	v_cmp_ge_f32_e64 s[6:7], 0, v71
	s_nop 1
	v_cndmask_b32_e64 v68, v68, v69, s[6:7]
	v_cmp_lt_f32_e64 s[6:7], 0, v72
	s_nop 1
	v_cndmask_b32_e64 v68, v68, v70, s[6:7]
	v_mul_f32_e32 v69, 0x37800000, v68
	v_cndmask_b32_e32 v68, v68, v69, vcc
	v_cmp_class_f32_e32 vcc, v65, v181
	s_nop 1
	v_cndmask_b32_e32 v65, v68, v65, vcc
	v_div_scale_f32 v68, s[6:7], v65, v65, 1.0
	v_rcp_f32_e32 v69, v68
	v_div_scale_f32 v70, vcc, 1.0, v65, 1.0
	v_fma_f32 v71, -v68, v69, 1.0
	v_fmac_f32_e32 v69, v71, v69
	v_mul_f32_e32 v71, v70, v69
	v_fma_f32 v72, -v68, v71, v70
	v_fmac_f32_e32 v71, v72, v69
	v_fma_f32 v68, -v68, v71, v70
	v_div_fmas_f32 v68, v68, v69, v71
	v_div_fixup_f32 v68, v68, v65, 1.0
.LBB0_2066:
	v_mul_lo_u32 v65, s59, v66
	v_mul_lo_u32 v69, s58, v67
	v_mad_u64_u32 v[66:67], s[6:7], s58, v66, 0
	v_add3_u32 v67, v67, v69, v65
	v_lshl_add_u64 v[66:67], v[66:67], 1, v[142:143]
	v_pk_mul_f32 v[62:63], v[62:63], v[68:69] op_sel_hi:[1,0]
	v_pk_mul_f32 v[60:61], v[60:61], v[68:69] op_sel_hi:[1,0]
	v_pk_mul_f32 v[70:71], v[58:59], v[68:69] op_sel_hi:[1,0]
	v_pk_mul_f32 v[58:59], v[56:57], v[68:69] op_sel_hi:[1,0]
	v_cvt_pk_bf16_f32 v56, v60, v61
	v_cvt_pk_bf16_f32 v57, v62, v63
	v_pk_mul_f32 v[52:53], v[52:53], v[68:69] op_sel_hi:[1,0]
	v_cvt_pk_bf16_f32 v58, v58, v59
	v_cvt_pk_bf16_f32 v59, v70, v71
	global_store_dwordx4 v[66:67], v[56:59], off
	v_pk_mul_f32 v[54:55], v[54:55], v[68:69] op_sel_hi:[1,0]
	s_and_b64 vcc, exec, s[4:5]
	v_pk_mul_f32 v[56:57], v[50:51], v[68:69] op_sel_hi:[1,0]
	v_pk_mul_f32 v[50:51], v[48:49], v[68:69] op_sel_hi:[1,0]
	v_cvt_pk_bf16_f32 v48, v52, v53
	v_cvt_pk_bf16_f32 v49, v54, v55
	s_nop 0
	v_cvt_pk_bf16_f32 v50, v50, v51
	v_cvt_pk_bf16_f32 v51, v56, v57
	global_store_dwordx4 v[66:67], v[48:51], off offset:256
	s_nop 1
	v_add_u32_e32 v48, 0x90, v140
	v_ashrrev_i32_e32 v49, 31, v48
	s_cbranch_vccnz .LBB0_2068
	v_lshl_add_u64 v[50:51], v[48:49], 3, s[20:21]
	v_mov_b32_e32 v50, v194
	v_fma_f32 v50, s27, v50, v180
	v_mul_f32_e32 v51, 0x4f800000, v50
	v_cmp_gt_f32_e32 vcc, s78, v50
	s_nop 1
	v_cndmask_b32_e32 v50, v50, v51, vcc
	v_sqrt_f32_e32 v51, v50
	s_nop 0
	v_add_u32_e32 v52, -1, v51
	v_add_u32_e32 v53, 1, v51
	v_fma_f32 v54, -v52, v51, v50
	v_fma_f32 v55, -v53, v51, v50
	v_cmp_ge_f32_e64 s[6:7], 0, v54
	s_nop 1
	v_cndmask_b32_e64 v51, v51, v52, s[6:7]
	v_cmp_lt_f32_e64 s[6:7], 0, v55
	s_nop 1
	v_cndmask_b32_e64 v51, v51, v53, s[6:7]
	v_mul_f32_e32 v52, 0x37800000, v51
	v_cndmask_b32_e32 v51, v51, v52, vcc
	v_cmp_class_f32_e32 vcc, v50, v181
	s_nop 1
	v_cndmask_b32_e32 v50, v51, v50, vcc
	v_div_scale_f32 v51, s[6:7], v50, v50, 1.0
	v_rcp_f32_e32 v52, v51
	v_div_scale_f32 v53, vcc, 1.0, v50, 1.0
	v_fma_f32 v54, -v51, v52, 1.0
	v_fmac_f32_e32 v52, v54, v52
	v_mul_f32_e32 v54, v53, v52
	v_fma_f32 v55, -v51, v54, v53
	v_fmac_f32_e32 v54, v55, v52
	v_fma_f32 v51, -v51, v54, v53
	v_div_fmas_f32 v51, v51, v52, v54
	v_div_fixup_f32 v64, v51, v50, 1.0
; DEV unsigned cvt_pk_bf16(float lo, float hi) { unsigned r; asm volatile("v_cvt_pk_bf16_f32 %0, %1, %2" : "=v"(r) : "v"(lo), "v"(hi)); return r; }
;     DEV void operator()(const Acc& acc, const Unit& u, int wr, int wc, int fr, int fq, LAS unsigned char*) const {
;     ...
;         for (int ai = 0; ai < 2; ++ai)
; #pragma unroll
;             for (int m = 0; m < 4; ++m) { const int row = row0 + ai * 128 + m * 16; bf16_t* rowp = base + (size_t)row * ldc + col0;
;                 const float sc = rs ? scale / sqrtf(rs[(size_t)row * 2 + rsi] * rsdiv + EPS) : scale;
; #pragma unroll
;                 for (int bj = 0; bj < 2; ++bj) { const f32x4 v0 = acc[ai][bj][m][0] * sc, v1 = acc[ai][bj][m][1] * sc; u32x4 w;
;                     w.x = cvt_pk_bf16(v0[0], v0[1]); w.y = cvt_pk_bf16(v0[2], v0[3]); w.z = cvt_pk_bf16(v1[0], v1[1]); w.w = cvt_pk_bf16(v1[2], v1[3]);
;                     *(u32x4*)(rowp + bj * 128) = w; } }
.LBB0_2068:
	v_mul_lo_u32 v50, s59, v48
	v_mul_lo_u32 v51, s58, v49
	v_mad_u64_u32 v[48:49], s[6:7], s58, v48, 0
	v_add3_u32 v49, v49, v51, v50
	v_lshl_add_u64 v[48:49], v[48:49], 1, v[142:143]
	v_pk_mul_f32 v[46:47], v[46:47], v[64:65] op_sel_hi:[1,0]
	v_pk_mul_f32 v[44:45], v[44:45], v[64:65] op_sel_hi:[1,0]
	v_pk_mul_f32 v[50:51], v[42:43], v[64:65] op_sel_hi:[1,0]
	v_pk_mul_f32 v[42:43], v[40:41], v[64:65] op_sel_hi:[1,0]
	v_cvt_pk_bf16_f32 v40, v44, v45
	v_cvt_pk_bf16_f32 v41, v46, v47
	v_pk_mul_f32 v[38:39], v[38:39], v[64:65] op_sel_hi:[1,0]
	v_cvt_pk_bf16_f32 v42, v42, v43
	v_cvt_pk_bf16_f32 v43, v50, v51
	global_store_dwordx4 v[48:49], v[40:43], off
	v_pk_mul_f32 v[36:37], v[36:37], v[64:65] op_sel_hi:[1,0]
	s_and_b64 vcc, exec, s[4:5]
	v_pk_mul_f32 v[40:41], v[34:35], v[64:65] op_sel_hi:[1,0]
	v_pk_mul_f32 v[34:35], v[32:33], v[64:65] op_sel_hi:[1,0]
	v_cvt_pk_bf16_f32 v32, v36, v37
	v_cvt_pk_bf16_f32 v33, v38, v39
	v_mov_b32_e32 v36, 1.0
	v_cvt_pk_bf16_f32 v34, v34, v35
	v_cvt_pk_bf16_f32 v35, v40, v41
	global_store_dwordx4 v[48:49], v[32:35], off offset:256
	s_nop 1
	v_add_u32_e32 v34, 0xa0, v140
	v_ashrrev_i32_e32 v35, 31, v34
	v_mov_b32_e32 v32, 1.0
	s_cbranch_vccnz .LBB0_2070
	v_lshl_add_u64 v[36:37], v[34:35], 3, s[20:21]
	v_mov_b32_e32 v33, v195
	v_fma_f32 v33, s27, v33, v180
	v_mul_f32_e32 v36, 0x4f800000, v33
	v_cmp_gt_f32_e32 vcc, s78, v33
	s_nop 1
	v_cndmask_b32_e32 v33, v33, v36, vcc
	v_sqrt_f32_e32 v36, v33
	s_nop 0
	v_add_u32_e32 v37, -1, v36
	v_add_u32_e32 v38, 1, v36
	v_fma_f32 v39, -v37, v36, v33
	v_fma_f32 v40, -v38, v36, v33
	v_cmp_ge_f32_e64 s[6:7], 0, v39
	s_nop 1
	v_cndmask_b32_e64 v36, v36, v37, s[6:7]
	v_cmp_lt_f32_e64 s[6:7], 0, v40
	s_nop 1
	v_cndmask_b32_e64 v36, v36, v38, s[6:7]
	v_mul_f32_e32 v37, 0x37800000, v36
	v_cndmask_b32_e32 v36, v36, v37, vcc
	v_cmp_class_f32_e32 vcc, v33, v181
	s_nop 1
	v_cndmask_b32_e32 v33, v36, v33, vcc
	v_div_scale_f32 v36, s[6:7], v33, v33, 1.0
	v_rcp_f32_e32 v37, v36
	v_div_scale_f32 v38, vcc, 1.0, v33, 1.0
	v_fma_f32 v39, -v36, v37, 1.0
	v_fmac_f32_e32 v37, v39, v37
	v_mul_f32_e32 v39, v38, v37
	v_fma_f32 v40, -v36, v39, v38
	v_fmac_f32_e32 v39, v40, v37
	v_fma_f32 v36, -v36, v39, v38
	v_div_fmas_f32 v36, v36, v37, v39
	v_div_fixup_f32 v36, v36, v33, 1.0
.LBB0_2070:
	v_mul_lo_u32 v33, s59, v34
	v_mul_lo_u32 v37, s58, v35
	v_mad_u64_u32 v[34:35], s[6:7], s58, v34, 0
	v_add3_u32 v35, v35, v37, v33
	v_lshl_add_u64 v[34:35], v[34:35], 1, v[142:143]
	v_pk_mul_f32 v[30:31], v[30:31], v[36:37] op_sel_hi:[1,0]
	v_pk_mul_f32 v[28:29], v[28:29], v[36:37] op_sel_hi:[1,0]
	v_pk_mul_f32 v[38:39], v[26:27], v[36:37] op_sel_hi:[1,0]
	v_pk_mul_f32 v[26:27], v[24:25], v[36:37] op_sel_hi:[1,0]
	v_cvt_pk_bf16_f32 v24, v28, v29
	v_cvt_pk_bf16_f32 v25, v30, v31
	v_pk_mul_f32 v[20:21], v[20:21], v[36:37] op_sel_hi:[1,0]
	v_cvt_pk_bf16_f32 v26, v26, v27
	v_cvt_pk_bf16_f32 v27, v38, v39
	global_store_dwordx4 v[34:35], v[24:27], off
	v_pk_mul_f32 v[22:23], v[22:23], v[36:37] op_sel_hi:[1,0]
	s_and_b64 vcc, exec, s[4:5]
	v_pk_mul_f32 v[24:25], v[18:19], v[36:37] op_sel_hi:[1,0]
	v_pk_mul_f32 v[18:19], v[16:17], v[36:37] op_sel_hi:[1,0]
	v_cvt_pk_bf16_f32 v16, v20, v21
	v_cvt_pk_bf16_f32 v17, v22, v23
	s_nop 0
	v_cvt_pk_bf16_f32 v18, v18, v19
	v_cvt_pk_bf16_f32 v19, v24, v25
	global_store_dwordx4 v[34:35], v[16:19], off offset:256
	s_nop 1
	v_add_u32_e32 v16, 0xb0, v140
	v_ashrrev_i32_e32 v17, 31, v16
	s_cbranch_vccnz .LBB0_2072
	v_lshl_add_u64 v[18:19], v[16:17], 3, s[20:21]
	v_mov_b32_e32 v18, v196
	v_fma_f32 v18, s27, v18, v180
	v_mul_f32_e32 v19, 0x4f800000, v18
	v_cmp_gt_f32_e32 vcc, s78, v18
	s_nop 1
	v_cndmask_b32_e32 v18, v18, v19, vcc
	v_sqrt_f32_e32 v19, v18
	s_nop 0
	v_add_u32_e32 v20, -1, v19
	v_add_u32_e32 v21, 1, v19
	v_fma_f32 v22, -v20, v19, v18
	v_fma_f32 v23, -v21, v19, v18
	v_cmp_ge_f32_e64 s[4:5], 0, v22
	s_nop 1
	v_cndmask_b32_e64 v19, v19, v20, s[4:5]
	v_cmp_lt_f32_e64 s[4:5], 0, v23
	s_nop 1
	v_cndmask_b32_e64 v19, v19, v21, s[4:5]
	v_mul_f32_e32 v20, 0x37800000, v19
	v_cndmask_b32_e32 v19, v19, v20, vcc
	v_cmp_class_f32_e32 vcc, v18, v181
	s_nop 1
	v_cndmask_b32_e32 v18, v19, v18, vcc
	v_div_scale_f32 v19, s[4:5], v18, v18, 1.0
	v_rcp_f32_e32 v20, v19
	v_div_scale_f32 v21, vcc, 1.0, v18, 1.0
	v_fma_f32 v22, -v19, v20, 1.0
	v_fmac_f32_e32 v20, v22, v20
	v_mul_f32_e32 v22, v21, v20
	v_fma_f32 v23, -v19, v22, v21
	v_fmac_f32_e32 v22, v23, v20
	v_fma_f32 v19, -v19, v22, v21
	v_div_fmas_f32 v19, v19, v20, v22
	v_div_fixup_f32 v32, v19, v18, 1.0
